# attention PV: key blocks 1..4 read one block ahead from eight fixed addresses + immediate offsets into alternating register sets, four MFMAs per block issued together
# speedup vs baseline: 1.0089x; 1.0028x over previous
; #define LAS __attribute__((address_space(3)))
; __device__ __forceinline__ void attn_phase(LAS unsigned char* lds, const bf16_t* QKVZ, const float* sinks, bf16_t* OG, int G, int bid, int tid) {
;     ...
;         for (int mt = 0; mt < 4; ++mt) {
;             const int qo0 = qh * 64 + mt * 16;
;             const size_t row = (size_t)(b * T + n * 128 + qo0 + fr);
;             const bf16_t* qp = QKVZ + row * ATT_IN + h * 64 + fq * 8;
;             const bf16x8 q0 = *(const bf16x8*)qp, q1 = *(const bf16x8*)(qp + 32);
;             const int kt0 = (qh * 4 + mt) < 6 ? (qh * 4 + mt) : 6;
;             f32x4 s[10];
; #pragma unroll
;             for (int kt = 0; kt < 10; ++kt) {
;                 const LAS unsigned char* kp = Kl + ((kt0 + kt) * 16 + fr) * KP + fq * 16;
;                 const bf16x8 k0 = *(const LAS bf16x8*)kp, k1 = *(const LAS bf16x8*)(kp + 64);
;                 f32x4 acc = (f32x4){0.f, 0.f, 0.f, 0.f};
;                 acc = __builtin_amdgcn_mfma_f32_16x16x32_bf16(k0, q0, acc, 0, 0, 0);
;                 acc = __builtin_amdgcn_mfma_f32_16x16x32_bf16(k1, q1, acc, 0, 0, 0);
;                 s[kt] = acc;
;             }
.Lmy_att_t0:
	v_add_u32_e32 v82, s1, v140
	v_mov_b64_e32 v[32:33], s[14:15]
	v_mad_i64_i32 v[84:85], s[26:27], v82, s22, v[32:33]
	v_lshl_add_u64 v[36:37], v[84:85], 0, v[72:73]
	v_mov_b64_e32 v[32:33], v[186:187]
	v_mov_b64_e32 v[34:35], v[188:189]
	v_mov_b64_e32 v[162:163], v[190:191]
	v_mov_b64_e32 v[164:165], v[192:193]
	s_mov_b32 s99, 0x14000
	s_cmp_eq_u32 s1, 48
	s_cselect_b32 s99, 0x27c4000, s99
	v_add_co_u32_e32 v194, vcc, s99, v36
	s_nop 1
	v_addc_co_u32_e32 v195, vcc, 0, v37, vcc
	global_load_dwordx4 v[186:189], v[194:195], off
	global_load_dwordx4 v[190:193], v[194:195], off offset:64
	v_lshlrev_b32_e32 v196, 1, v76
	v_mov_b32_e32 v197, v73
	v_lshl_add_u64 v[198:199], v[84:85], 0, v[196:197]
	global_load_dwordx2 v[200:201], v[198:199], off offset:3072
	global_load_dwordx2 v[202:203], v[198:199], off offset:3104
	global_load_dwordx2 v[204:205], v[198:199], off offset:3136
	global_load_dwordx2 v[206:207], v[198:199], off offset:3168
	s_min_u32 s25, s8, 6
	s_lshl_b32 s25, s25, 4
	s_add_i32 s26, s25, 16
	s_add_i32 s29, s25, 32
	s_add_i32 s28, s25, 64
	s_add_i32 s27, s25, 0x60
	s_add_i32 s30, s25, 0x90
	s_add_i32 s26, s25, 48
	s_add_i32 s26, s25, 0x50
	s_add_i32 s26, s25, 0x70
	s_or_b32 s26, s25, 0x80
	v_or_b32_e32 v248, s25, v89
	v_mad_u32_u24 v248, v248, s19, v90
	ds_read_b128 v[208:211], v248
	ds_read_b128 v[212:215], v248 offset:64
	ds_read_b128 v[216:219], v248 offset:2304
	ds_read_b128 v[220:223], v248 offset:2368
	ds_read_b128 v[224:227], v248 offset:4608
	ds_read_b128 v[228:231], v248 offset:4672
	ds_read_b128 v[232:235], v248 offset:6912
	ds_read_b128 v[236:239], v248 offset:6976
	ds_read_b128 v[240:243], v248 offset:9216
	ds_read_b128 v[244:247], v248 offset:9280
	v_subrev_u32_e32 v185, s25, v129
	v_add_u32_e32 v146, s25, v139
	v_subrev_u32_e32 v180, s25, v118
	v_subrev_u32_e32 v179, s25, v117
	v_subrev_u32_e32 v184, s25, v128
	v_subrev_u32_e32 v178, s25, v116
	v_subrev_u32_e32 v175, s25, v107
	v_subrev_u32_e32 v183, s25, v127
	v_subrev_u32_e32 v177, s25, v115
	v_subrev_u32_e32 v174, s25, v106
	v_subrev_u32_e32 v182, s25, v126
	v_subrev_u32_e32 v176, s25, v114
	v_subrev_u32_e32 v161, s25, v105
	v_subrev_u32_e32 v181, s25, v125
	v_subrev_u32_e32 v159, s25, v113
	v_subrev_u32_e32 v158, s25, v104
	v_subrev_u32_e32 v160, s25, v124
	v_subrev_u32_e32 v156, s25, v112
	v_subrev_u32_e32 v155, s25, v103
	v_subrev_u32_e32 v157, s25, v123
	v_subrev_u32_e32 v152, s25, v111
	v_subrev_u32_e32 v151, s25, v102
	v_subrev_u32_e32 v153, s25, v122
	v_subrev_u32_e32 v149, s25, v110
	v_subrev_u32_e32 v147, s25, v101
	v_subrev_u32_e32 v150, s25, v121
	v_subrev_u32_e32 v145, s25, v109
	v_subrev_u32_e32 v144, s25, v100
	v_subrev_u32_e32 v148, s25, v120
	v_subrev_u32_e32 v143, s25, v108
	v_subrev_u32_e32 v142, s25, v98
	v_ashrrev_i32_e32 v83, 31, v82
	v_add_u32_e32 v139, -16, v139
	s_waitcnt lgkmcnt(8)
	v_mfma_f32_16x16x32_bf16 v[68:71], v[208:211], v[32:35], 0
	v_mfma_f32_16x16x32_bf16 v[68:71], v[212:215], v[162:165], v[68:71]
	s_waitcnt lgkmcnt(6)
	v_mfma_f32_16x16x32_bf16 v[64:67], v[216:219], v[32:35], 0
	v_mfma_f32_16x16x32_bf16 v[64:67], v[220:223], v[162:165], v[64:67]
	ds_read_b128 v[208:211], v248 offset:11520
	ds_read_b128 v[212:215], v248 offset:11584
	s_waitcnt lgkmcnt(6)
	v_mfma_f32_16x16x32_bf16 v[60:63], v[224:227], v[32:35], 0
	v_mfma_f32_16x16x32_bf16 v[60:63], v[228:231], v[162:165], v[60:63]
	ds_read_b128 v[216:219], v248 offset:13824
	ds_read_b128 v[220:223], v248 offset:13888
	s_waitcnt lgkmcnt(6)
	v_mfma_f32_16x16x32_bf16 v[56:59], v[232:235], v[32:35], 0
	v_mfma_f32_16x16x32_bf16 v[56:59], v[236:239], v[162:165], v[56:59]
	ds_read_b128 v[224:227], v248 offset:16128
	ds_read_b128 v[228:231], v248 offset:16192
	s_waitcnt lgkmcnt(6)
	v_mfma_f32_16x16x32_bf16 v[52:55], v[240:243], v[32:35], 0
	v_mfma_f32_16x16x32_bf16 v[52:55], v[244:247], v[162:165], v[52:55]
	ds_read_b128 v[232:235], v248 offset:18432
	ds_read_b128 v[236:239], v248 offset:18496
	s_waitcnt lgkmcnt(6)
	v_mfma_f32_16x16x32_bf16 v[48:51], v[208:211], v[32:35], 0
	v_mfma_f32_16x16x32_bf16 v[48:51], v[212:215], v[162:165], v[48:51]
	ds_read_b128 v[240:243], v248 offset:20736
	ds_read_b128 v[244:247], v248 offset:20800
	s_waitcnt lgkmcnt(6)
	v_mfma_f32_16x16x32_bf16 v[44:47], v[216:219], v[32:35], 0
	v_mfma_f32_16x16x32_bf16 v[44:47], v[220:223], v[162:165], v[44:47]
	s_waitcnt lgkmcnt(4)
	v_mfma_f32_16x16x32_bf16 v[40:43], v[224:227], v[32:35], 0
	v_mfma_f32_16x16x32_bf16 v[40:43], v[228:231], v[162:165], v[40:43]
	s_waitcnt lgkmcnt(2)
	v_mfma_f32_16x16x32_bf16 v[36:39], v[232:235], v[32:35], 0
	v_mfma_f32_16x16x32_bf16 v[36:39], v[236:239], v[162:165], v[36:39]
	s_waitcnt lgkmcnt(0)
; __device__ __forceinline__ void attn_phase(LAS unsigned char* lds, const bf16_t* QKVZ, const float* sinks, bf16_t* OG, int G, int bid, int tid) {
;     ...
;             const int qi = 128 + qo0 + fr;
;             float mx = sink2;
; #pragma unroll
;             for (int kt = 0; kt < 10; ++kt)
; #pragma unroll
;                 for (int r = 0; r < 4; ++r) { const int si = (kt0 + kt) * 16 + 4 * fq + r, df = qi - si; const bool ok = (df >= 0) && (df < 128) && (n > 0 || si >= 128);
;                     const float v = ok ? s[kt][r] : -1e30f; s[kt][r] = v; mx = fmaxf(mx, v); }
;             mx = fmaxf(mx, __shfl_xor(mx, 16)); mx = fmaxf(mx, __shfl_xor(mx, 32));
	v_mfma_f32_16x16x32_bf16 v[32:35], v[240:243], v[32:35], 0
	v_mfma_f32_16x16x32_bf16 v[32:35], v[244:247], v[162:165], v[32:35]
	v_or_b32_e32 v154, s25, v76
	v_add_u32_e32 v162, s1, v99
	v_add_u32_e32 v163, v162, v185
	v_cmp_gt_u32_e32 vcc, s20, v163
	s_and_b64 vcc, s[12:13], vcc
	v_add_u32_e32 v163, 0xffffff80, v146
	v_cndmask_b32_e32 v68, v138, v68, vcc
	v_cmp_lt_u32_e32 vcc, s23, v163
	s_and_b64 vcc, s[12:13], vcc
	v_add_u32_e32 v164, v162, v180
	v_cndmask_b32_e32 v69, v138, v69, vcc
	v_cmp_gt_u32_e32 vcc, s20, v164
	s_and_b64 vcc, s[12:13], vcc
	v_add_u32_e32 v164, v162, v179
	v_cndmask_b32_e32 v70, v138, v70, vcc
	v_cmp_gt_u32_e32 vcc, s20, v164
	s_and_b64 vcc, s[12:13], vcc
	v_add_u32_e32 v164, v162, v184
	v_cndmask_b32_e32 v71, v138, v71, vcc
	v_cmp_gt_u32_e32 vcc, s20, v164
	s_and_b64 vcc, s[12:13], vcc
	v_add_u32_e32 v164, 0xffffff90, v146
	v_cndmask_b32_e32 v64, v138, v64, vcc
	v_cmp_lt_u32_e32 vcc, s23, v164
	s_and_b64 vcc, s[12:13], vcc
	v_add_u32_e32 v164, v162, v178
	v_cndmask_b32_e32 v65, v138, v65, vcc
	v_cmp_gt_u32_e32 vcc, s20, v164
	s_and_b64 vcc, s[12:13], vcc
	v_add_u32_e32 v164, v162, v175
	v_cndmask_b32_e32 v66, v138, v66, vcc
	v_cmp_gt_u32_e32 vcc, s20, v164
	s_and_b64 vcc, s[12:13], vcc
	s_cmp_gt_u32 s8, 5
	v_add_u32_e32 v165, v162, v183
	s_cselect_b64 s[30:31], -1, 0
	v_cndmask_b32_e32 v67, v138, v67, vcc
	v_cmp_gt_u32_e32 vcc, s20, v165
	s_or_b64 s[30:31], s[12:13], s[30:31]
	s_and_b64 vcc, vcc, s[30:31]
	v_add_u32_e32 v165, 0xffffffa0, v146
	v_cndmask_b32_e32 v60, v138, v60, vcc
	v_cmp_lt_u32_e32 vcc, s23, v165
	s_and_b64 vcc, vcc, s[30:31]
	v_add_u32_e32 v165, v162, v177
	v_cndmask_b32_e32 v61, v138, v61, vcc
	v_cmp_gt_u32_e32 vcc, s20, v165
	s_and_b64 vcc, vcc, s[30:31]
	v_add_u32_e32 v165, v162, v174
	v_cndmask_b32_e32 v62, v138, v62, vcc
	v_cmp_gt_u32_e32 vcc, s20, v165
	s_and_b64 vcc, vcc, s[30:31]
	s_cmp_gt_u32 s8, 4
	v_add_u32_e32 v165, v162, v182
	s_cselect_b64 s[30:31], -1, 0
	v_cndmask_b32_e32 v63, v138, v63, vcc
	v_cmp_gt_u32_e32 vcc, s20, v165
	s_or_b64 s[30:31], s[12:13], s[30:31]
	s_and_b64 vcc, vcc, s[30:31]
	v_add_u32_e32 v165, 0xffffffb0, v146
	v_cndmask_b32_e32 v56, v138, v56, vcc
	v_cmp_lt_u32_e32 vcc, s23, v165
	s_and_b64 vcc, vcc, s[30:31]
	v_add_u32_e32 v165, v162, v176
	v_cndmask_b32_e32 v57, v138, v57, vcc
	v_cmp_gt_u32_e32 vcc, s20, v165
	s_and_b64 vcc, vcc, s[30:31]
	v_add_u32_e32 v161, v162, v161
	v_cndmask_b32_e32 v58, v138, v58, vcc
	v_cmp_gt_u32_e32 vcc, s20, v161
	s_and_b64 vcc, vcc, s[30:31]
	s_cmp_gt_u32 s8, 3
	v_add_u32_e32 v165, v162, v181
	s_cselect_b64 s[30:31], -1, 0
	v_cndmask_b32_e32 v59, v138, v59, vcc
	v_cmp_gt_u32_e32 vcc, s20, v165
	s_or_b64 s[30:31], s[12:13], s[30:31]
	s_and_b64 vcc, vcc, s[30:31]
	v_subrev_u32_e32 v165, 64, v146
	v_cndmask_b32_e32 v52, v138, v52, vcc
	v_cmp_lt_u32_e32 vcc, s23, v165
	s_and_b64 vcc, vcc, s[30:31]
	v_add_u32_e32 v159, v162, v159
	v_cndmask_b32_e32 v53, v138, v53, vcc
	v_cmp_gt_u32_e32 vcc, s20, v159
	s_and_b64 vcc, vcc, s[30:31]
	v_add_u32_e32 v158, v162, v158
	v_cndmask_b32_e32 v54, v138, v54, vcc
	v_cmp_gt_u32_e32 vcc, s20, v158
	s_and_b64 vcc, vcc, s[30:31]
	s_cmp_gt_u32 s8, 2
	v_add_u32_e32 v159, v162, v160
	s_cselect_b64 s[30:31], -1, 0
	v_cndmask_b32_e32 v55, v138, v55, vcc
	v_cmp_gt_u32_e32 vcc, s20, v159
	s_or_b64 s[30:31], s[12:13], s[30:31]
	s_and_b64 vcc, vcc, s[30:31]
	v_subrev_u32_e32 v159, 48, v146
	v_cndmask_b32_e32 v48, v138, v48, vcc
	v_cmp_lt_u32_e32 vcc, s23, v159
	s_and_b64 vcc, vcc, s[30:31]
	v_add_u32_e32 v156, v162, v156
	v_cndmask_b32_e32 v49, v138, v49, vcc
	v_cmp_gt_u32_e32 vcc, s20, v156
	s_and_b64 vcc, vcc, s[30:31]
	v_add_u32_e32 v155, v162, v155
	v_cndmask_b32_e32 v50, v138, v50, vcc
	v_cmp_gt_u32_e32 vcc, s20, v155
	s_and_b64 vcc, vcc, s[30:31]
	s_cmp_gt_u32 s8, 1
	v_add_u32_e32 v157, v162, v157
	s_cselect_b64 s[30:31], -1, 0
	v_cndmask_b32_e32 v51, v138, v51, vcc
	v_cmp_gt_u32_e32 vcc, s20, v157
	s_or_b64 s[30:31], s[12:13], s[30:31]
	s_and_b64 vcc, vcc, s[30:31]
	v_subrev_u32_e32 v157, 32, v146
	v_cndmask_b32_e32 v44, v138, v44, vcc
	v_cmp_lt_u32_e32 vcc, s23, v157
	s_and_b64 vcc, vcc, s[30:31]
	v_add_u32_e32 v152, v162, v152
	v_cndmask_b32_e32 v45, v138, v45, vcc
	v_cmp_gt_u32_e32 vcc, s20, v152
	s_and_b64 vcc, vcc, s[30:31]
	v_add_u32_e32 v151, v162, v151
	v_cndmask_b32_e32 v46, v138, v46, vcc
	v_cmp_gt_u32_e32 vcc, s20, v151
	v_max3_f32 v163, v141, v68, v69
	s_and_b64 vcc, vcc, s[30:31]
	s_or_b32 s30, s8, s0
	v_max3_f32 v163, v163, v70, v71
	v_add_u32_e32 v152, v162, v153
	s_cmp_lg_u32 s30, 0
	v_max3_f32 v163, v163, v64, v65
	v_cndmask_b32_e32 v47, v138, v47, vcc
	v_cmp_gt_u32_e32 vcc, s20, v152
	s_cselect_b64 s[30:31], -1, 0
	v_max3_f32 v163, v163, v66, v67
	s_and_b64 vcc, s[30:31], vcc
	v_add_u32_e32 v152, -16, v146
	v_max3_f32 v163, v163, v60, v61
	v_cndmask_b32_e32 v40, v138, v40, vcc
	v_cmp_lt_u32_e32 vcc, s23, v152
	v_max3_f32 v163, v163, v62, v63
	s_and_b64 vcc, s[30:31], vcc
	v_add_u32_e32 v149, v162, v149
	v_max3_f32 v163, v163, v56, v57
	v_cndmask_b32_e32 v41, v138, v41, vcc
	v_cmp_gt_u32_e32 vcc, s20, v149
	v_max3_f32 v161, v163, v58, v59
	s_and_b64 vcc, s[30:31], vcc
	v_add_u32_e32 v147, v162, v147
	v_max3_f32 v161, v161, v52, v53
	v_cndmask_b32_e32 v42, v138, v42, vcc
	v_cmp_gt_u32_e32 vcc, s20, v147
	v_max3_f32 v158, v161, v54, v55
	s_and_b64 vcc, s[30:31], vcc
	v_add_u32_e32 v150, v162, v150
	v_max3_f32 v158, v158, v48, v49
	v_cndmask_b32_e32 v43, v138, v43, vcc
	v_cmp_gt_u32_e32 vcc, s20, v150
	v_max3_f32 v155, v158, v50, v51
	v_add_u32_e32 v145, v162, v145
	v_cndmask_b32_e32 v36, v138, v36, vcc
	v_cmp_lt_u32_e32 vcc, s23, v146
	v_max3_f32 v155, v155, v44, v45
	v_add_u32_e32 v144, v162, v144
	v_cndmask_b32_e32 v37, v138, v37, vcc
	v_cmp_gt_u32_e32 vcc, s20, v145
	v_max3_f32 v151, v155, v46, v47
	v_add_u32_e32 v145, v162, v148
	v_cndmask_b32_e32 v38, v138, v38, vcc
	v_cmp_gt_u32_e32 vcc, s20, v144
	v_max3_f32 v151, v151, v40, v41
	v_max3_f32 v147, v151, v42, v43
	v_cndmask_b32_e32 v39, v138, v39, vcc
	v_cmp_gt_u32_e32 vcc, s20, v145
	v_add_u32_e32 v145, 16, v146
	v_add_u32_e32 v143, v162, v143
	v_cndmask_b32_e32 v32, v138, v32, vcc
	v_cmp_lt_u32_e32 vcc, s23, v145
	v_max3_f32 v147, v147, v36, v37
	v_add_u32_e32 v142, v162, v142
	v_cndmask_b32_e32 v33, v138, v33, vcc
	v_cmp_gt_u32_e32 vcc, s20, v143
	v_max3_f32 v144, v147, v38, v39
	v_max3_f32 v144, v144, v32, v33
	v_cndmask_b32_e32 v34, v138, v34, vcc
	v_cmp_gt_u32_e32 vcc, s20, v142
	v_or_b32_e32 v164, s29, v76
	v_or_b32_e32 v163, s28, v76
	v_cndmask_b32_e32 v35, v138, v35, vcc
	v_max3_f32 v142, v144, v34, v35
	ds_bpermute_b32 v143, v91, v142
	v_or_b32_e32 v156, s27, v76
	v_or_b32_e32 v149, s26, v76
	s_add_i32 s1, s1, 16
	s_add_i32 s8, s8, 1
	s_waitcnt lgkmcnt(0)
; __device__ __forceinline__ u32x4 pack8(const f32x4 a, const f32x4 b) { u32x4 w; w.x = cvt_pk_bf16(a[0], a[1]); w.y = cvt_pk_bf16(a[2], a[3]); w.z = cvt_pk_bf16(b[0], b[1]); w.w = cvt_pk_bf16(b[2], b[3]); return w; }
; #define LAS __attribute__((address_space(3)))
; __device__ __forceinline__ void attn_phase(LAS unsigned char* lds, const bf16_t* QKVZ, const float* sinks, bf16_t* OG, int G, int bid, int tid) {
;     ...
;             for (int kt = 0; kt < 10; ++kt)
; #pragma unroll
;                 for (int r = 0; r < 4; ++r) { const float p = __builtin_amdgcn_exp2f(s[kt][r] - mx); s[kt][r] = p; sum += p; }
;             sum += __shfl_xor(sum, 16); sum += __shfl_xor(sum, 32);
;             sum += __builtin_amdgcn_exp2f(sink2 - mx);
;             const float inv = 1.0f / sum;
;             f32x4 o[4];
; #pragma unroll
;             for (int dt = 0; dt < 4; ++dt) o[dt] = (f32x4){0.f, 0.f, 0.f, 0.f};
; #pragma unroll
;             for (int kk = 0; kk < 5; ++kk) {
;                 const u32x4 pw = pack8(s[2 * kk], s[2 * kk + 1]);
;                 const bf16x8 pf = __builtin_bit_cast(bf16x8, pw);
; #pragma unroll
;                 for (int dt = 0; dt < 4; ++dt) {
;                     const int d = dt * 16 + fr, sw = ((d >> 3) & 7) << 2, keyA = 16 * (kt0 + 2 * kk) + 4 * fq, keyB = keyA + 16;
;                     const u32x2 va = *(const LAS u32x2*)(Vt + d * VP + ((keyA ^ sw) * 2)), vb = *(const LAS u32x2*)(Vt + d * VP + ((keyB ^ sw) * 2));
;                     const u32x4 vw = (u32x4){va.x, va.y, vb.x, vb.y};
;                     o[dt] = __builtin_amdgcn_mfma_f32_16x16x32_bf16(__builtin_bit_cast(bf16x8, vw), pf, o[dt], 0, 0, 0);
	v_max_f32_e32 v143, v143, v143
	v_max_f32_e32 v142, v142, v143
	ds_bpermute_b32 v143, v92, v142
	s_cmp_eq_u32 s1, 64
	s_waitcnt lgkmcnt(0)
	v_max_f32_e32 v143, v143, v143
	v_max_f32_e32 v142, v142, v143
	v_sub_f32_e32 v68, v68, v142
	v_exp_f32_e32 v68, v68
	v_sub_f32_e32 v69, v69, v142
	v_exp_f32_e32 v69, v69
	v_sub_f32_e32 v70, v70, v142
	v_exp_f32_e32 v70, v70
	v_sub_f32_e32 v71, v71, v142
	v_exp_f32_e32 v71, v71
	v_sub_f32_e32 v64, v64, v142
	v_add_f32_e32 v143, 0, v68
	v_exp_f32_e32 v64, v64
	v_sub_f32_e32 v65, v65, v142
	v_add_f32_e32 v143, v69, v143
	v_exp_f32_e32 v65, v65
	v_sub_f32_e32 v66, v66, v142
	v_add_f32_e32 v143, v70, v143
	v_exp_f32_e32 v66, v66
	v_sub_f32_e32 v67, v67, v142
	v_add_f32_e32 v143, v71, v143
	v_exp_f32_e32 v67, v67
	v_sub_f32_e32 v60, v60, v142
	v_add_f32_e32 v143, v64, v143
	v_exp_f32_e32 v60, v60
	v_sub_f32_e32 v61, v61, v142
	v_add_f32_e32 v143, v65, v143
	v_exp_f32_e32 v61, v61
	v_sub_f32_e32 v62, v62, v142
	v_add_f32_e32 v143, v66, v143
	v_exp_f32_e32 v62, v62
	v_sub_f32_e32 v63, v63, v142
	v_add_f32_e32 v143, v67, v143
	v_exp_f32_e32 v63, v63
	v_sub_f32_e32 v56, v56, v142
	v_add_f32_e32 v143, v60, v143
	v_exp_f32_e32 v56, v56
	v_sub_f32_e32 v57, v57, v142
	v_add_f32_e32 v143, v61, v143
	v_exp_f32_e32 v57, v57
	v_sub_f32_e32 v58, v58, v142
	v_add_f32_e32 v143, v62, v143
	v_exp_f32_e32 v58, v58
	v_sub_f32_e32 v59, v59, v142
	v_add_f32_e32 v143, v63, v143
	v_exp_f32_e32 v59, v59
	v_sub_f32_e32 v52, v52, v142
	v_add_f32_e32 v143, v56, v143
	v_exp_f32_e32 v144, v52
	v_add_f32_e32 v143, v57, v143
	v_add_f32_e32 v143, v58, v143
	v_add_f32_e32 v143, v59, v143
	v_sub_f32_e32 v53, v53, v142
	v_add_f32_e32 v52, v144, v143
	v_exp_f32_e32 v143, v53
	v_sub_f32_e32 v53, v54, v142
	v_exp_f32_e32 v145, v53
	v_sub_f32_e32 v53, v55, v142
	v_exp_f32_e32 v146, v53
	v_sub_f32_e32 v48, v48, v142
	v_exp_f32_e32 v147, v48
	v_sub_f32_e32 v49, v49, v142
	v_add_f32_e32 v52, v143, v52
	v_exp_f32_e32 v148, v49
	v_sub_f32_e32 v49, v50, v142
	v_add_f32_e32 v52, v145, v52
	v_exp_f32_e32 v150, v49
	v_sub_f32_e32 v49, v51, v142
	v_add_f32_e32 v52, v146, v52
	v_exp_f32_e32 v151, v49
	v_sub_f32_e32 v44, v44, v142
	v_add_f32_e32 v48, v147, v52
	v_exp_f32_e32 v152, v44
	v_sub_f32_e32 v45, v45, v142
	v_add_f32_e32 v48, v148, v48
	v_exp_f32_e32 v153, v45
	v_sub_f32_e32 v45, v46, v142
	v_add_f32_e32 v48, v150, v48
	v_exp_f32_e32 v155, v45
	v_sub_f32_e32 v45, v47, v142
	v_add_f32_e32 v48, v151, v48
	v_exp_f32_e32 v157, v45
	v_sub_f32_e32 v40, v40, v142
	v_add_f32_e32 v44, v152, v48
	v_exp_f32_e32 v158, v40
	v_sub_f32_e32 v41, v41, v142
	v_add_f32_e32 v44, v153, v44
	v_exp_f32_e32 v159, v41
	v_sub_f32_e32 v41, v42, v142
	v_add_f32_e32 v44, v155, v44
	v_exp_f32_e32 v160, v41
	v_sub_f32_e32 v41, v43, v142
	v_add_f32_e32 v44, v157, v44
	v_exp_f32_e32 v161, v41
	v_sub_f32_e32 v36, v36, v142
	v_add_f32_e32 v40, v158, v44
	v_exp_f32_e32 v162, v36
	v_sub_f32_e32 v37, v37, v142
	v_add_f32_e32 v40, v159, v40
	v_exp_f32_e32 v165, v37
	v_sub_f32_e32 v37, v38, v142
	v_add_f32_e32 v40, v160, v40
	v_exp_f32_e32 v166, v37
	v_sub_f32_e32 v37, v39, v142
	v_add_f32_e32 v40, v161, v40
	v_exp_f32_e32 v167, v37
	v_sub_f32_e32 v32, v32, v142
	v_add_f32_e32 v36, v162, v40
	v_exp_f32_e32 v168, v32
	v_sub_f32_e32 v33, v33, v142
	v_add_f32_e32 v36, v165, v36
	v_exp_f32_e32 v169, v33
	v_sub_f32_e32 v33, v34, v142
	v_add_f32_e32 v36, v166, v36
	v_exp_f32_e32 v170, v33
	v_sub_f32_e32 v33, v35, v142
	v_add_f32_e32 v36, v167, v36
	v_exp_f32_e32 v171, v33
	v_add_f32_e32 v32, v168, v36
	v_add_f32_e32 v32, v169, v32
	v_add_f32_e32 v32, v170, v32
	v_add_f32_e32 v32, v171, v32
	ds_bpermute_b32 v33, v91, v32
	v_add_u32_e32 v50, 16, v154
	v_bitop3_b32 v36, s25, v93, v76 bitop3:0x36
	v_xor_b32_e32 v38, v50, v93
	v_bitop3_b32 v40, s25, v95, v76 bitop3:0x36
	s_waitcnt lgkmcnt(0)
	v_add_f32_e32 v32, v32, v33
	ds_bpermute_b32 v33, v92, v32
	v_xor_b32_e32 v42, v50, v95
	v_bitop3_b32 v44, s25, v96, v76 bitop3:0x36
	v_xor_b32_e32 v46, v50, v96
	v_bitop3_b32 v48, s25, v97, v76 bitop3:0x36
	s_waitcnt lgkmcnt(0)
	v_add_f32_e32 v32, v32, v33
	v_sub_f32_e32 v33, v141, v142
	v_exp_f32_e32 v33, v33
	v_xor_b32_e32 v50, v50, v97
	v_lshl_add_u32 v36, v36, 1, v94
	v_lshl_add_u32 v38, v38, 1, v94
	v_lshl_add_u32 v40, v40, 1, v94
	v_lshl_add_u32 v42, v42, 1, v94
	v_lshl_add_u32 v44, v44, 1, v94
	v_lshl_add_u32 v46, v46, 1, v94
	v_lshl_add_u32 v48, v48, 1, v94
	v_lshl_add_u32 v50, v50, 1, v94
	v_mov_b32_e32 v208, v36
	v_mov_b32_e32 v209, v38
	v_mov_b32_e32 v210, v40
	v_mov_b32_e32 v211, v42
	v_mov_b32_e32 v212, v44
	v_mov_b32_e32 v213, v46
	v_mov_b32_e32 v214, v48
	v_mov_b32_e32 v215, v50
	v_add_f32_e32 v142, v33, v32
	v_cvt_pk_bf16_f32 v32, v68, v69
	v_cvt_pk_bf16_f32 v33, v70, v71
	v_cvt_pk_bf16_f32 v34, v64, v65
	v_cvt_pk_bf16_f32 v35, v66, v67
	ds_read_b64 v[36:37], v36 offset:36864
	ds_read_b64 v[38:39], v38 offset:36864
	ds_read_b64 v[40:41], v40 offset:45312
	ds_read_b64 v[42:43], v42 offset:45312
	ds_read_b64 v[44:45], v44 offset:53760
	ds_read_b64 v[46:47], v46 offset:53760
	ds_read_b64 v[48:49], v48 offset:62208
	ds_read_b64 v[50:51], v50 offset:62208
	ds_read_b64 v[232:233], v208 offset:36928
	ds_read_b64 v[234:235], v209 offset:36928
	ds_read_b64 v[236:237], v210 offset:45376
	ds_read_b64 v[238:239], v211 offset:45376
	ds_read_b64 v[240:241], v212 offset:53824
	ds_read_b64 v[242:243], v213 offset:53824
	ds_read_b64 v[244:245], v214 offset:62272
	ds_read_b64 v[246:247], v215 offset:62272
	s_waitcnt lgkmcnt(14)
	v_mfma_f32_16x16x32_bf16 v[36:39], v[36:39], v[32:35], 0
	v_bitop3_b32 v52, s29, v93, v76 bitop3:0x36
	v_lshl_add_u32 v52, v52, 1, v94
	s_waitcnt lgkmcnt(12)
; __device__ __forceinline__ u32x4 pack8(const f32x4 a, const f32x4 b) { u32x4 w; w.x = cvt_pk_bf16(a[0], a[1]); w.y = cvt_pk_bf16(a[2], a[3]); w.z = cvt_pk_bf16(b[0], b[1]); w.w = cvt_pk_bf16(b[2], b[3]); return w; }
; #define LAS __attribute__((address_space(3)))
; __device__ __forceinline__ void attn_phase(LAS unsigned char* lds, const bf16_t* QKVZ, const float* sinks, bf16_t* OG, int G, int bid, int tid) {
;     ...
;             const float inv = 1.0f / sum;
;             f32x4 o[4];
;     ...
;             for (int kk = 0; kk < 5; ++kk) {
;                 const u32x4 pw = pack8(s[2 * kk], s[2 * kk + 1]);
;                 const bf16x8 pf = __builtin_bit_cast(bf16x8, pw);
; #pragma unroll
;                 for (int dt = 0; dt < 4; ++dt) {
;                     const int d = dt * 16 + fr, sw = ((d >> 3) & 7) << 2, keyA = 16 * (kt0 + 2 * kk) + 4 * fq, keyB = keyA + 16;
;                     const u32x2 va = *(const LAS u32x2*)(Vt + d * VP + ((keyA ^ sw) * 2)), vb = *(const LAS u32x2*)(Vt + d * VP + ((keyB ^ sw) * 2));
;                     const u32x4 vw = (u32x4){va.x, va.y, vb.x, vb.y};
;                     o[dt] = __builtin_amdgcn_mfma_f32_16x16x32_bf16(__builtin_bit_cast(bf16x8, vw), pf, o[dt], 0, 0, 0);
;                 }
;             }
	v_mfma_f32_16x16x32_bf16 v[40:43], v[40:43], v[32:35], 0
	s_waitcnt lgkmcnt(10)
	v_mfma_f32_16x16x32_bf16 v[44:47], v[44:47], v[32:35], 0
	s_waitcnt lgkmcnt(8)
	v_mfma_f32_16x16x32_bf16 v[32:35], v[48:51], v[32:35], 0
	v_cvt_pk_bf16_f32 v48, v60, v61
	v_cvt_pk_bf16_f32 v49, v62, v63
	v_cvt_pk_bf16_f32 v50, v56, v57
	v_cvt_pk_bf16_f32 v51, v58, v59
	s_nop 1
	ds_read_b64 v[216:217], v208 offset:36992
	ds_read_b64 v[218:219], v209 offset:36992
	ds_read_b64 v[220:221], v210 offset:45440
	ds_read_b64 v[222:223], v211 offset:45440
	ds_read_b64 v[224:225], v212 offset:53888
	ds_read_b64 v[226:227], v213 offset:53888
	ds_read_b64 v[228:229], v214 offset:62336
	ds_read_b64 v[230:231], v215 offset:62336
	s_waitcnt lgkmcnt(8)
	v_mfma_f32_16x16x32_bf16 v[36:39], v[232:235], v[48:51], v[36:39]
	v_mfma_f32_16x16x32_bf16 v[40:43], v[236:239], v[48:51], v[40:43]
	v_mfma_f32_16x16x32_bf16 v[44:47], v[240:243], v[48:51], v[44:47]
	v_mfma_f32_16x16x32_bf16 v[32:35], v[244:247], v[48:51], v[32:35]
	v_cvt_pk_bf16_f32 v248, v144, v143
	v_cvt_pk_bf16_f32 v249, v145, v146
	v_cvt_pk_bf16_f32 v250, v147, v148
	v_cvt_pk_bf16_f32 v251, v150, v151
	s_nop 1
	ds_read_b64 v[232:233], v208 offset:37056
	ds_read_b64 v[234:235], v209 offset:37056
	ds_read_b64 v[236:237], v210 offset:45504
	ds_read_b64 v[238:239], v211 offset:45504
	ds_read_b64 v[240:241], v212 offset:53952
	ds_read_b64 v[242:243], v213 offset:53952
	ds_read_b64 v[244:245], v214 offset:62400
	ds_read_b64 v[246:247], v215 offset:62400
	s_waitcnt lgkmcnt(8)
	v_mfma_f32_16x16x32_bf16 v[36:39], v[216:219], v[248:251], v[36:39]
	v_mfma_f32_16x16x32_bf16 v[40:43], v[220:223], v[248:251], v[40:43]
	v_mfma_f32_16x16x32_bf16 v[44:47], v[224:227], v[248:251], v[44:47]
	v_mfma_f32_16x16x32_bf16 v[32:35], v[228:231], v[248:251], v[32:35]
	v_cvt_pk_bf16_f32 v48, v152, v153
	v_cvt_pk_bf16_f32 v49, v155, v157
	v_cvt_pk_bf16_f32 v50, v158, v159
	v_cvt_pk_bf16_f32 v51, v160, v161
	s_nop 1
	ds_read_b64 v[216:217], v208 offset:37120
	ds_read_b64 v[218:219], v209 offset:37120
	ds_read_b64 v[220:221], v210 offset:45568
	ds_read_b64 v[222:223], v211 offset:45568
	ds_read_b64 v[224:225], v212 offset:54016
	ds_read_b64 v[226:227], v213 offset:54016
	ds_read_b64 v[228:229], v214 offset:62464
	ds_read_b64 v[230:231], v215 offset:62464
	s_waitcnt lgkmcnt(8)
	v_mfma_f32_16x16x32_bf16 v[36:39], v[232:235], v[48:51], v[36:39]
	v_mfma_f32_16x16x32_bf16 v[40:43], v[236:239], v[48:51], v[40:43]
	v_mfma_f32_16x16x32_bf16 v[52:55], v[240:243], v[48:51], v[44:47]
	v_mfma_f32_16x16x32_bf16 v[32:35], v[244:247], v[48:51], v[32:35]
	v_cvt_pk_bf16_f32 v248, v162, v165
	v_cvt_pk_bf16_f32 v249, v166, v167
	v_cvt_pk_bf16_f32 v250, v168, v169
	v_cvt_pk_bf16_f32 v251, v170, v171
	s_nop 1
	s_waitcnt lgkmcnt(0)
	v_mfma_f32_16x16x32_bf16 v[44:47], v[216:219], v[248:251], v[36:39]
	v_mfma_f32_16x16x32_bf16 v[40:43], v[220:223], v[248:251], v[40:43]
	v_mfma_f32_16x16x32_bf16 v[36:39], v[224:227], v[248:251], v[52:55]
	v_mfma_f32_16x16x32_bf16 v[32:35], v[228:231], v[248:251], v[32:35]
	v_div_scale_f32 v48, s[26:27], v142, v142, 1.0
	v_rcp_f32_e32 v49, v48
	s_nop 0
	v_fma_f32 v50, -v48, v49, 1.0
	v_fmac_f32_e32 v49, v50, v49
	v_div_scale_f32 v50, vcc, 1.0, v142, 1.0
	v_mul_f32_e32 v51, v50, v49
	v_fma_f32 v52, -v48, v51, v50
	v_fmac_f32_e32 v51, v52, v49
	v_fma_f32 v48, -v48, v51, v50
	v_div_fmas_f32 v48, v48, v49, v51
	v_div_fixup_f32 v52, v48, v142, 1.0
	v_lshlrev_b32_e32 v48, 1, v76
	v_mov_b32_e32 v49, v73
	v_lshl_add_u64 v[50:51], v[84:85], 0, v[48:49]
	v_mul_f32_e32 v44, v52, v44
	v_mul_f32_e32 v45, v52, v45
	v_mul_f32_e32 v46, v52, v46
	v_mul_f32_e32 v47, v52, v47
	v_lshlrev_b64 v[48:49], 11, v[82:83]
	v_lshl_add_u64 v[48:49], v[80:81], 0, v[48:49]
	v_mul_f32_e32 v41, v52, v41
	v_mul_f32_e32 v40, v52, v40
	v_mul_f32_e32 v42, v52, v42
	v_mul_f32_e32 v43, v52, v43
	v_mul_f32_e32 v37, v52, v37
	v_mul_f32_e32 v36, v52, v36
	v_mul_f32_e32 v38, v52, v38
	v_mul_f32_e32 v39, v52, v39
	v_mul_f32_e32 v33, v52, v33
	v_mul_f32_e32 v32, v52, v32
	v_mul_f32_e32 v34, v52, v34
	v_mul_f32_e32 v35, v52, v35
	s_waitcnt vmcnt(0)
; __device__ __forceinline__ unsigned cvt_pk_bf16(float lo, float hi) { unsigned r; asm volatile("v_cvt_pk_bf16_f32 %0, %1, %2" : "=v"(r) : "v"(lo), "v"(hi)); return r; }
; __device__ __forceinline__ float bflo(unsigned w) { return __uint_as_float(w << 16); }
; __device__ __forceinline__ float bfhi(unsigned w) { return __uint_as_float(w & 0xffff0000u); }
; __device__ __forceinline__ float fsigmoid(float x) { return __builtin_amdgcn_rcpf(1.0f + __expf(-x)); }
; __device__ __forceinline__ void attn_phase(LAS unsigned char* lds, const bf16_t* QKVZ, const float* sinks, bf16_t* OG, int G, int bid, int tid) {
;     ...
;             const bf16_t* zp = QKVZ + row * ATT_IN + 1536 + h * 64 + 4 * fq;
;             bf16_t* op = OG + row * D + h * 64 + 4 * fq;
; #pragma unroll
;             for (int dt = 0; dt < 4; ++dt) {
;                 const u32x2 zw = *(const u32x2*)(zp + dt * 16);
;                 const float z0 = bflo(zw.x), z1 = bfhi(zw.x), z2 = bflo(zw.y), z3 = bfhi(zw.y);
;                 const float r0 = o[dt][0] * inv * z0 * fsigmoid(z0), r1 = o[dt][1] * inv * z1 * fsigmoid(z1), r2 = o[dt][2] * inv * z2 * fsigmoid(z2), r3 = o[dt][3] * inv * z3 * fsigmoid(z3);
;                 u32x2 w; w.x = cvt_pk_bf16(r0, r1); w.y = cvt_pk_bf16(r2, r3);
;                 *(u32x2*)(op + dt * 16) = w;
;             }
;         }
	v_mov_b64_e32 v[54:55], v[200:201]
	v_lshlrev_b32_e32 v53, 16, v54
	v_mul_f32_e32 v44, v44, v53
	v_mul_f32_e32 v53, 0xbfb8aa3b, v53
	v_exp_f32_e32 v53, v53
	v_and_b32_e32 v54, 0xffff0000, v54
	v_lshlrev_b32_e32 v56, 16, v55
	v_mul_f32_e32 v45, v45, v54
	v_add_f32_e32 v53, 1.0, v53
	v_rcp_f32_e32 v53, v53
	v_and_b32_e32 v55, 0xffff0000, v55
	v_mul_f32_e32 v46, v46, v56
	v_mul_f32_e32 v47, v47, v55
	v_mul_f32_e32 v44, v44, v53
	v_mul_f32_e32 v53, 0xbfb8aa3b, v54
	v_exp_f32_e32 v53, v53
	s_nop 0
	v_add_f32_e32 v53, 1.0, v53
	v_rcp_f32_e32 v53, v53
	s_nop 0
	v_mul_f32_e32 v45, v45, v53
	v_mul_f32_e32 v53, 0xbfb8aa3b, v56
	v_exp_f32_e32 v53, v53
	v_cvt_pk_bf16_f32 v44, v44, v45
	s_nop 0
	v_add_f32_e32 v53, 1.0, v53
	v_rcp_f32_e32 v53, v53
	s_nop 0
	v_mul_f32_e32 v46, v46, v53
	v_mul_f32_e32 v53, 0xbfb8aa3b, v55
	v_exp_f32_e32 v53, v53
	s_nop 0
	v_add_f32_e32 v53, 1.0, v53
	v_rcp_f32_e32 v53, v53
	s_nop 0
	v_mul_f32_e32 v47, v47, v53
	v_cvt_pk_bf16_f32 v45, v46, v47
	global_store_dwordx2 v[48:49], v[44:45], off
	s_nop 1
	v_mov_b64_e32 v[44:45], v[202:203]
	v_lshlrev_b32_e32 v46, 16, v44
	v_and_b32_e32 v44, 0xffff0000, v44
	v_mul_f32_e32 v41, v41, v44
	v_mul_f32_e32 v44, 0xbfb8aa3b, v44
	v_exp_f32_e32 v44, v44
	v_lshlrev_b32_e32 v47, 16, v45
	v_and_b32_e32 v45, 0xffff0000, v45
	v_mul_f32_e32 v40, v40, v46
	v_add_f32_e32 v44, 1.0, v44
	v_rcp_f32_e32 v44, v44
	v_mul_f32_e32 v46, 0xbfb8aa3b, v46
	v_mul_f32_e32 v42, v42, v47
	v_exp_f32_e32 v46, v46
	v_mul_f32_e32 v41, v41, v44
	v_mul_f32_e32 v44, 0xbfb8aa3b, v47
	v_exp_f32_e32 v44, v44
	v_add_f32_e32 v46, 1.0, v46
	v_rcp_f32_e32 v46, v46
	v_mul_f32_e32 v43, v43, v45
	v_add_f32_e32 v44, 1.0, v44
	v_rcp_f32_e32 v44, v44
	v_mul_f32_e32 v40, v40, v46
	v_cvt_pk_bf16_f32 v40, v40, v41
	v_mul_f32_e32 v42, v42, v44
	v_mul_f32_e32 v44, 0xbfb8aa3b, v45
	v_exp_f32_e32 v44, v44
	s_nop 0
	v_add_f32_e32 v44, 1.0, v44
	v_rcp_f32_e32 v44, v44
	s_nop 0
	v_mul_f32_e32 v43, v43, v44
	v_cvt_pk_bf16_f32 v41, v42, v43
	global_store_dwordx2 v[48:49], v[40:41], off offset:32
	s_nop 1
	v_mov_b64_e32 v[40:41], v[204:205]
	v_lshlrev_b32_e32 v42, 16, v40
	v_and_b32_e32 v40, 0xffff0000, v40
	v_mul_f32_e32 v37, v37, v40
	v_mul_f32_e32 v40, 0xbfb8aa3b, v40
	v_exp_f32_e32 v40, v40
	v_lshlrev_b32_e32 v43, 16, v41
	v_and_b32_e32 v41, 0xffff0000, v41
	v_mul_f32_e32 v36, v36, v42
	v_add_f32_e32 v40, 1.0, v40
	v_rcp_f32_e32 v40, v40
	v_mul_f32_e32 v42, 0xbfb8aa3b, v42
	v_mul_f32_e32 v38, v38, v43
	v_exp_f32_e32 v42, v42
	v_mul_f32_e32 v37, v37, v40
	v_mul_f32_e32 v40, 0xbfb8aa3b, v43
	v_exp_f32_e32 v40, v40
	v_add_f32_e32 v42, 1.0, v42
	v_rcp_f32_e32 v42, v42
	v_mul_f32_e32 v39, v39, v41
	v_add_f32_e32 v40, 1.0, v40
	v_rcp_f32_e32 v40, v40
	v_mul_f32_e32 v36, v36, v42
	v_cvt_pk_bf16_f32 v36, v36, v37
	v_mul_f32_e32 v38, v38, v40
	v_mul_f32_e32 v40, 0xbfb8aa3b, v41
	v_exp_f32_e32 v40, v40
	s_nop 0
	v_add_f32_e32 v40, 1.0, v40
	v_rcp_f32_e32 v40, v40
	s_nop 0
	v_mul_f32_e32 v39, v39, v40
	v_cvt_pk_bf16_f32 v37, v38, v39
	global_store_dwordx2 v[48:49], v[36:37], off offset:64
	s_nop 1
	v_mov_b64_e32 v[36:37], v[206:207]
	v_lshlrev_b32_e32 v38, 16, v36
	v_and_b32_e32 v36, 0xffff0000, v36
	v_mul_f32_e32 v33, v33, v36
	v_mul_f32_e32 v36, 0xbfb8aa3b, v36
	v_exp_f32_e32 v36, v36
	v_lshlrev_b32_e32 v39, 16, v37
	v_and_b32_e32 v37, 0xffff0000, v37
	v_mul_f32_e32 v32, v32, v38
	v_add_f32_e32 v36, 1.0, v36
	v_rcp_f32_e32 v36, v36
	v_mul_f32_e32 v38, 0xbfb8aa3b, v38
	v_mul_f32_e32 v34, v34, v39
	v_exp_f32_e32 v38, v38
	v_mul_f32_e32 v33, v33, v36
	v_mul_f32_e32 v36, 0xbfb8aa3b, v39
	v_exp_f32_e32 v36, v36
	v_add_f32_e32 v38, 1.0, v38
	v_rcp_f32_e32 v38, v38
	v_mul_f32_e32 v35, v35, v37
	v_add_f32_e32 v36, 1.0, v36
	v_rcp_f32_e32 v36, v36
	v_mul_f32_e32 v32, v32, v38
	v_cvt_pk_bf16_f32 v32, v32, v33
	v_mul_f32_e32 v34, v34, v36
	v_mul_f32_e32 v36, 0xbfb8aa3b, v37
	v_exp_f32_e32 v36, v36
	s_nop 0
	v_add_f32_e32 v36, 1.0, v36
	v_rcp_f32_e32 v36, v36
	s_nop 0
	v_mul_f32_e32 v35, v35, v36
	v_cvt_pk_bf16_f32 v33, v34, v35
	global_store_dwordx2 v[48:49], v[32:33], off offset:96
	s_cbranch_scc0 .LBB0_246
	s_add_i32 s16, s16, s21
	s_and_b64 vcc, exec, s[10:11]
	s_mov_b32 s12, s24
	s_cbranch_vccz .LBB0_235
